# out-projection epilogue: accumulator registers of finished row groups reused as landing buffers (more residual loads in flight), with write-through stores
# baseline (speedup 1.0000x reference)
;     __device__ __forceinline__ void operator()(const f32x4 (&acc)[2][2][4][2], const pg8::Unit& u, int wr, int wc, int fr, int fq) const {
;     ...
;         const float* gp = gatev + (size_t)(u.pm >> 3) * 3072 + col0;
;         f32x4 gv[2][2];
; #pragma unroll
;         for (int bj = 0; bj < 2; ++bj)
; #pragma unroll
;             for (int n = 0; n < 2; ++n) gv[bj][n] = *(const f32x4*)(gp + bj * 128 + n * 16);
; #pragma unroll
;         for (int ai = 0; ai < 2; ++ai)
; #pragma unroll
;             for (int m = 0; m < 4; ++m) {
;                 const size_t off = (size_t)(row0 + ai * 128 + m * 16) * DM + col0;
; #pragma unroll
;                 for (int bj = 0; bj < 2; ++bj)
; #pragma unroll
;                     for (int n = 0; n < 2; ++n) {
;                         const f32x4 xv = *(const f32x4*)(xin + off + bj * 128 + n * 16);
;                         *(f32x4*)(out + off + bj * 128 + n * 16) = xv + gv[bj][n] * acc[ai][bj][m][n];
;                     }
;                 if (m == 3) asm volatile("" ::: "memory");
;             }
.LBB0_582:
	v_lshl_add_u32 v170, s30, 8, v158
	v_lshl_or_b32 v168, s56, 8, v160
	s_ashr_i32 s23, s30, 3
	v_ashrrev_i32_e32 v171, 31, v170
	s_mul_hi_i32 s25, s23, 0x3000
	s_mulk_i32 s23, 0x3000
	v_ashrrev_i32_e32 v169, 31, v168
	v_lshlrev_b64 v[130:131], 10, v[170:171]
	s_add_u32 s34, s49, s23
	v_lshl_add_u64 v[130:131], v[130:131], 0, v[168:169]
	s_addc_u32 s35, s50, s25
	v_lshlrev_b64 v[156:157], 2, v[130:131]
	v_lshl_add_u64 v[128:129], v[168:169], 2, s[34:35]
	v_and_b32_e32 v165, 0xffffff00, v170
	v_and_b32_e32 v166, 15, v170
	v_lshl_add_u32 v165, v166, 3, v165
	v_bfe_u32 v166, v170, 6, 1
	v_lshl_add_u32 v165, v166, 2, v165
	v_lshlrev_b32_e32 v165, 12, v165
	v_lshl_add_u32 v156, v168, 2, v165
	global_load_dwordx4 v[140:143], v[128:129], off
	global_load_dwordx4 v[136:139], v[128:129], off offset:64
	global_load_dwordx4 v[132:135], v[128:129], off offset:512
	s_nop 0
	global_load_dwordx4 v[128:131], v[128:129], off offset:576
	s_andn2_b64 vcc, exec, s[4:5]
	s_mov_b64 s[4:5], -1
	s_mov_b64 s[36:37], s[0:1]
	global_load_dwordx4 v[164:167], v156, s[36:37]
	global_load_dwordx4 v[168:171], v156, s[36:37] offset:64
	global_load_dwordx4 v[172:175], v156, s[36:37] offset:512
	global_load_dwordx4 v[176:179], v156, s[36:37] offset:576
	s_add_u32 s36, s0, 0x1000
	s_addc_u32 s37, s1, 0
	global_load_dwordx4 v[180:183], v156, s[36:37]
	global_load_dwordx4 v[184:187], v156, s[36:37] offset:64
	global_load_dwordx4 v[188:191], v156, s[36:37] offset:512
	global_load_dwordx4 v[192:195], v156, s[36:37] offset:576
	s_add_u32 s36, s0, 0x2000
	s_addc_u32 s37, s1, 0
	global_load_dwordx4 v[196:199], v156, s[36:37]
	global_load_dwordx4 v[204:207], v156, s[36:37] offset:64
	global_load_dwordx4 v[208:211], v156, s[36:37] offset:512
	global_load_dwordx4 v[212:215], v156, s[36:37] offset:576
	s_waitcnt vmcnt(8)
	v_pk_fma_f32 v[166:167], v[126:127], v[142:143], v[166:167]
	v_pk_fma_f32 v[164:165], v[124:125], v[140:141], v[164:165]
	v_pk_fma_f32 v[170:171], v[122:123], v[138:139], v[170:171]
	v_pk_fma_f32 v[168:169], v[120:121], v[136:137], v[168:169]
	v_pk_fma_f32 v[174:175], v[118:119], v[134:135], v[174:175]
	v_pk_fma_f32 v[172:173], v[116:117], v[132:133], v[172:173]
	v_pk_fma_f32 v[178:179], v[106:107], v[130:131], v[178:179]
	v_pk_fma_f32 v[176:177], v[104:105], v[128:129], v[176:177]
	s_add_u32 s36, s0, 0x3000
	s_addc_u32 s37, s1, 0
	global_load_dwordx4 v[124:127], v156, s[36:37]
	global_load_dwordx4 v[120:123], v156, s[36:37] offset:64
	global_load_dwordx4 v[116:119], v156, s[36:37] offset:512
	global_load_dwordx4 v[104:107], v156, s[36:37] offset:576
	s_mov_b64 s[38:39], s[8:9]
	global_store_dwordx4 v156, v[164:167], s[38:39] sc1
	global_store_dwordx4 v156, v[168:171], s[38:39] offset:64 sc1
	global_store_dwordx4 v156, v[172:175], s[38:39] offset:512 sc1
	global_store_dwordx4 v156, v[176:179], s[38:39] offset:576 sc1
	s_add_u32 s36, s0, 0x80000
	s_addc_u32 s37, s1, 0
	global_load_dwordx4 v[164:167], v156, s[36:37]
	global_load_dwordx4 v[168:171], v156, s[36:37] offset:64
	global_load_dwordx4 v[172:175], v156, s[36:37] offset:512
	global_load_dwordx4 v[176:179], v156, s[36:37] offset:576
	s_waitcnt vmcnt(16)
	v_pk_fma_f32 v[182:183], v[114:115], v[142:143], v[182:183]
	v_pk_fma_f32 v[180:181], v[112:113], v[140:141], v[180:181]
	v_pk_fma_f32 v[186:187], v[110:111], v[138:139], v[186:187]
	v_pk_fma_f32 v[184:185], v[108:109], v[136:137], v[184:185]
	v_pk_fma_f32 v[190:191], v[102:103], v[134:135], v[190:191]
	v_pk_fma_f32 v[188:189], v[100:101], v[132:133], v[188:189]
	v_pk_fma_f32 v[194:195], v[90:91], v[130:131], v[194:195]
	v_pk_fma_f32 v[192:193], v[88:89], v[128:129], v[192:193]
	s_add_u32 s36, s0, 0x81000
	s_addc_u32 s37, s1, 0
	global_load_dwordx4 v[112:115], v156, s[36:37]
	global_load_dwordx4 v[108:111], v156, s[36:37] offset:64
	global_load_dwordx4 v[100:103], v156, s[36:37] offset:512
	global_load_dwordx4 v[88:91], v156, s[36:37] offset:576
	s_add_u32 s38, s8, 0x1000
	s_addc_u32 s39, s9, 0
	global_store_dwordx4 v156, v[180:183], s[38:39] sc1
	global_store_dwordx4 v156, v[184:187], s[38:39] offset:64 sc1
	global_store_dwordx4 v156, v[188:191], s[38:39] offset:512 sc1
	global_store_dwordx4 v156, v[192:195], s[38:39] offset:576 sc1
	s_add_u32 s36, s0, 0x82000
	s_addc_u32 s37, s1, 0
	global_load_dwordx4 v[180:183], v156, s[36:37]
	global_load_dwordx4 v[184:187], v156, s[36:37] offset:64
	global_load_dwordx4 v[188:191], v156, s[36:37] offset:512
	global_load_dwordx4 v[192:195], v156, s[36:37] offset:576
	s_waitcnt vmcnt(24)
;     __device__ __forceinline__ void operator()(const f32x4 (&acc)[2][2][4][2], const pg8::Unit& u, int wr, int wc, int fr, int fq) const {
;     ...
;         for (int ai = 0; ai < 2; ++ai)
; #pragma unroll
;             for (int m = 0; m < 4; ++m) {
;                 const size_t off = (size_t)(row0 + ai * 128 + m * 16) * DM + col0;
; #pragma unroll
;                 for (int bj = 0; bj < 2; ++bj)
; #pragma unroll
;                     for (int n = 0; n < 2; ++n) {
;                         const f32x4 xv = *(const f32x4*)(xin + off + bj * 128 + n * 16);
;                         *(f32x4*)(out + off + bj * 128 + n * 16) = xv + gv[bj][n] * acc[ai][bj][m][n];
;                     }
;                 if (m == 3) asm volatile("" ::: "memory");
;             }
	v_pk_fma_f32 v[198:199], v[98:99], v[142:143], v[198:199]
	v_pk_fma_f32 v[196:197], v[96:97], v[140:141], v[196:197]
	v_pk_fma_f32 v[206:207], v[94:95], v[138:139], v[206:207]
	v_pk_fma_f32 v[204:205], v[92:93], v[136:137], v[204:205]
	v_pk_fma_f32 v[210:211], v[86:87], v[134:135], v[210:211]
	v_pk_fma_f32 v[208:209], v[84:85], v[132:133], v[208:209]
	v_pk_fma_f32 v[214:215], v[74:75], v[130:131], v[214:215]
	v_pk_fma_f32 v[212:213], v[72:73], v[128:129], v[212:213]
	s_add_u32 s36, s0, 0x83000
	s_addc_u32 s37, s1, 0
	global_load_dwordx4 v[96:99], v156, s[36:37]
	global_load_dwordx4 v[92:95], v156, s[36:37] offset:64
	global_load_dwordx4 v[84:87], v156, s[36:37] offset:512
	global_load_dwordx4 v[72:75], v156, s[36:37] offset:576
	s_add_u32 s38, s8, 0x2000
	s_addc_u32 s39, s9, 0
	global_store_dwordx4 v156, v[196:199], s[38:39] sc1
	global_store_dwordx4 v156, v[204:207], s[38:39] offset:64 sc1
	global_store_dwordx4 v156, v[208:211], s[38:39] offset:512 sc1
	global_store_dwordx4 v156, v[212:215], s[38:39] offset:576 sc1
	s_waitcnt vmcnt(28)
	v_pk_fma_f32 v[126:127], v[82:83], v[142:143], v[126:127]
	v_pk_fma_f32 v[124:125], v[80:81], v[140:141], v[124:125]
	v_pk_fma_f32 v[122:123], v[78:79], v[138:139], v[122:123]
	v_pk_fma_f32 v[120:121], v[76:77], v[136:137], v[120:121]
	v_pk_fma_f32 v[118:119], v[70:71], v[134:135], v[118:119]
	v_pk_fma_f32 v[116:117], v[68:69], v[132:133], v[116:117]
	v_pk_fma_f32 v[106:107], v[66:67], v[130:131], v[106:107]
	v_pk_fma_f32 v[104:105], v[64:65], v[128:129], v[104:105]
	s_add_u32 s38, s8, 0x3000
	s_addc_u32 s39, s9, 0
	global_store_dwordx4 v156, v[124:127], s[38:39] sc1
	global_store_dwordx4 v156, v[120:123], s[38:39] offset:64 sc1
	global_store_dwordx4 v156, v[116:119], s[38:39] offset:512 sc1
	global_store_dwordx4 v156, v[104:107], s[38:39] offset:576 sc1
	s_waitcnt vmcnt(24)
	v_pk_fma_f32 v[166:167], v[62:63], v[142:143], v[166:167]
	v_pk_fma_f32 v[164:165], v[60:61], v[140:141], v[164:165]
	v_pk_fma_f32 v[170:171], v[58:59], v[138:139], v[170:171]
	v_pk_fma_f32 v[168:169], v[56:57], v[136:137], v[168:169]
	v_pk_fma_f32 v[174:175], v[54:55], v[134:135], v[174:175]
	v_pk_fma_f32 v[172:173], v[52:53], v[132:133], v[172:173]
	v_pk_fma_f32 v[178:179], v[42:43], v[130:131], v[178:179]
	v_pk_fma_f32 v[176:177], v[40:41], v[128:129], v[176:177]
	s_add_u32 s38, s8, 0x80000
	s_addc_u32 s39, s9, 0
	global_store_dwordx4 v156, v[164:167], s[38:39] sc1
	global_store_dwordx4 v156, v[168:171], s[38:39] offset:64 sc1
	global_store_dwordx4 v156, v[172:175], s[38:39] offset:512 sc1
	global_store_dwordx4 v156, v[176:179], s[38:39] offset:576 sc1
	s_waitcnt vmcnt(24)
	v_pk_fma_f32 v[114:115], v[50:51], v[142:143], v[114:115]
	v_pk_fma_f32 v[112:113], v[48:49], v[140:141], v[112:113]
	v_pk_fma_f32 v[110:111], v[46:47], v[138:139], v[110:111]
	v_pk_fma_f32 v[108:109], v[44:45], v[136:137], v[108:109]
	v_pk_fma_f32 v[102:103], v[38:39], v[134:135], v[102:103]
	v_pk_fma_f32 v[100:101], v[36:37], v[132:133], v[100:101]
	v_pk_fma_f32 v[90:91], v[26:27], v[130:131], v[90:91]
	v_pk_fma_f32 v[88:89], v[24:25], v[128:129], v[88:89]
	s_add_u32 s38, s8, 0x81000
	s_addc_u32 s39, s9, 0
	global_store_dwordx4 v156, v[112:115], s[38:39] sc1
	global_store_dwordx4 v156, v[108:111], s[38:39] offset:64 sc1
	global_store_dwordx4 v156, v[100:103], s[38:39] offset:512 sc1
	global_store_dwordx4 v156, v[88:91], s[38:39] offset:576 sc1
	s_waitcnt vmcnt(20)
	v_pk_fma_f32 v[182:183], v[34:35], v[142:143], v[182:183]
	v_pk_fma_f32 v[180:181], v[32:33], v[140:141], v[180:181]
	v_pk_fma_f32 v[186:187], v[30:31], v[138:139], v[186:187]
	v_pk_fma_f32 v[184:185], v[28:29], v[136:137], v[184:185]
	v_pk_fma_f32 v[190:191], v[22:23], v[134:135], v[190:191]
	v_pk_fma_f32 v[188:189], v[20:21], v[132:133], v[188:189]
	v_pk_fma_f32 v[194:195], v[10:11], v[130:131], v[194:195]
	v_pk_fma_f32 v[192:193], v[8:9], v[128:129], v[192:193]
	s_add_u32 s38, s8, 0x82000
	s_addc_u32 s39, s9, 0
	global_store_dwordx4 v156, v[180:183], s[38:39] sc1
	global_store_dwordx4 v156, v[184:187], s[38:39] offset:64 sc1
	global_store_dwordx4 v156, v[188:191], s[38:39] offset:512 sc1
	global_store_dwordx4 v156, v[192:195], s[38:39] offset:576 sc1
	s_waitcnt vmcnt(20)
	v_pk_fma_f32 v[98:99], v[18:19], v[142:143], v[98:99]
	v_pk_fma_f32 v[96:97], v[16:17], v[140:141], v[96:97]
	v_pk_fma_f32 v[94:95], v[14:15], v[138:139], v[94:95]
	v_pk_fma_f32 v[92:93], v[12:13], v[136:137], v[92:93]
	v_pk_fma_f32 v[86:87], v[6:7], v[134:135], v[86:87]
	v_pk_fma_f32 v[84:85], v[4:5], v[132:133], v[84:85]
	v_pk_fma_f32 v[74:75], v[2:3], v[130:131], v[74:75]
	v_pk_fma_f32 v[72:73], v[0:1], v[128:129], v[72:73]
	s_add_u32 s38, s8, 0x83000
	s_addc_u32 s39, s9, 0
	global_store_dwordx4 v156, v[96:99], s[38:39] sc1
	global_store_dwordx4 v156, v[92:95], s[38:39] offset:64 sc1
	global_store_dwordx4 v156, v[84:87], s[38:39] offset:512 sc1
	global_store_dwordx4 v156, v[72:75], s[38:39] offset:576 sc1
	s_cbranch_vccnz .LBB0_571
	s_andn2_b64 vcc, exec, s[6:7]
	s_cbranch_vccnz .LBB0_570
	s_barrier
	s_branch .LBB0_570

;     __device__ __forceinline__ void operator()(const f32x4 (&acc)[2][2][4][2], const pg8::Unit& u, int wr, int wc, int fr, int fq) const {
;     ...
;         const float* gp = gatev + (size_t)(u.pm >> 3) * 3072 + col0;
;         f32x4 gv[2][2];
; #pragma unroll
;         for (int bj = 0; bj < 2; ++bj)
; #pragma unroll
;             for (int n = 0; n < 2; ++n) gv[bj][n] = *(const f32x4*)(gp + bj * 128 + n * 16);
; #pragma unroll
;         for (int ai = 0; ai < 2; ++ai)
; #pragma unroll
;             for (int m = 0; m < 4; ++m) {
;                 const size_t off = (size_t)(row0 + ai * 128 + m * 16) * DM + col0;
; #pragma unroll
;                 for (int bj = 0; bj < 2; ++bj)
; #pragma unroll
;                     for (int n = 0; n < 2; ++n) {
;                         const f32x4 xv = *(const f32x4*)(xin + off + bj * 128 + n * 16);
;                         *(f32x4*)(out + off + bj * 128 + n * 16) = xv + gv[bj][n] * acc[ai][bj][m][n];
;                     }
;                 if (m == 3) asm volatile("" ::: "memory");
;             }
.LBB0_1107:
	s_ashr_i32 s21, s28, 3
	v_lshl_or_b32 v128, s58, 8, v160
	s_mul_hi_i32 s23, s21, 0x3000
	s_mulk_i32 s21, 0x3000
	v_lshl_add_u32 v216, s28, 8, v158
	s_add_u32 s30, s47, s21
	v_ashrrev_i32_e32 v129, 31, v128
	s_addc_u32 s31, s48, s23
	v_lshlrev_b64 v[200:201], 2, v[128:129]
	v_lshl_add_u64 v[136:137], s[30:31], 0, v[200:201]
	v_and_b32_e32 v165, 0xffffff00, v216
	v_and_b32_e32 v166, 15, v216
	v_lshl_add_u32 v165, v166, 3, v165
	v_bfe_u32 v166, v216, 6, 1
	v_lshl_add_u32 v165, v166, 2, v165
	v_lshlrev_b32_e32 v156, 12, v165
	v_add_u32_e32 v156, v156, v200
	global_load_dwordx4 v[132:135], v[136:137], off
	global_load_dwordx4 v[128:131], v[136:137], off offset:64
	global_load_dwordx4 v[140:143], v[136:137], off offset:512
	s_nop 0
	global_load_dwordx4 v[136:139], v[136:137], off offset:576
	s_andn2_b64 vcc, exec, s[0:1]
	s_mov_b64 s[0:1], -1
	s_mov_b64 s[34:35], s[4:5]
	global_load_dwordx4 v[164:167], v156, s[34:35]
	global_load_dwordx4 v[168:171], v156, s[34:35] offset:64
	global_load_dwordx4 v[172:175], v156, s[34:35] offset:512
	global_load_dwordx4 v[176:179], v156, s[34:35] offset:576
	s_add_u32 s34, s4, 0x1000
	s_addc_u32 s35, s5, 0
	global_load_dwordx4 v[180:183], v156, s[34:35]
	global_load_dwordx4 v[184:187], v156, s[34:35] offset:64
	global_load_dwordx4 v[188:191], v156, s[34:35] offset:512
	global_load_dwordx4 v[192:195], v156, s[34:35] offset:576
	s_add_u32 s34, s4, 0x2000
	s_addc_u32 s35, s5, 0
	global_load_dwordx4 v[196:199], v156, s[34:35]
	global_load_dwordx4 v[204:207], v156, s[34:35] offset:64
	global_load_dwordx4 v[208:211], v156, s[34:35] offset:512
	global_load_dwordx4 v[212:215], v156, s[34:35] offset:576
	s_waitcnt vmcnt(8)
	v_pk_fma_f32 v[166:167], v[126:127], v[134:135], v[166:167]
	v_pk_fma_f32 v[164:165], v[124:125], v[132:133], v[164:165]
	v_pk_fma_f32 v[170:171], v[122:123], v[130:131], v[170:171]
	v_pk_fma_f32 v[168:169], v[120:121], v[128:129], v[168:169]
	v_pk_fma_f32 v[174:175], v[106:107], v[142:143], v[174:175]
	v_pk_fma_f32 v[172:173], v[104:105], v[140:141], v[172:173]
	v_pk_fma_f32 v[178:179], v[98:99], v[138:139], v[178:179]
	v_pk_fma_f32 v[176:177], v[96:97], v[136:137], v[176:177]
	s_add_u32 s34, s4, 0x3000
	s_addc_u32 s35, s5, 0
	global_load_dwordx4 v[124:127], v156, s[34:35]
	global_load_dwordx4 v[120:123], v156, s[34:35] offset:64
	global_load_dwordx4 v[104:107], v156, s[34:35] offset:512
	global_load_dwordx4 v[96:99], v156, s[34:35] offset:576
	s_mov_b64 s[36:37], s[4:5]
	global_store_dwordx4 v156, v[164:167], s[36:37] sc1
	global_store_dwordx4 v156, v[168:171], s[36:37] offset:64 sc1
	global_store_dwordx4 v156, v[172:175], s[36:37] offset:512 sc1
	global_store_dwordx4 v156, v[176:179], s[36:37] offset:576 sc1
	s_add_u32 s34, s4, 0x80000
	s_addc_u32 s35, s5, 0
	global_load_dwordx4 v[164:167], v156, s[34:35]
	global_load_dwordx4 v[168:171], v156, s[34:35] offset:64
	global_load_dwordx4 v[172:175], v156, s[34:35] offset:512
	global_load_dwordx4 v[176:179], v156, s[34:35] offset:576
	s_waitcnt vmcnt(16)
	v_pk_fma_f32 v[182:183], v[118:119], v[134:135], v[182:183]
	v_pk_fma_f32 v[180:181], v[116:117], v[132:133], v[180:181]
	v_pk_fma_f32 v[186:187], v[114:115], v[130:131], v[186:187]
	v_pk_fma_f32 v[184:185], v[112:113], v[128:129], v[184:185]
	v_pk_fma_f32 v[190:191], v[90:91], v[142:143], v[190:191]
	v_pk_fma_f32 v[188:189], v[88:89], v[140:141], v[188:189]
	v_pk_fma_f32 v[194:195], v[86:87], v[138:139], v[194:195]
	v_pk_fma_f32 v[192:193], v[84:85], v[136:137], v[192:193]
	s_add_u32 s34, s4, 0x81000
	s_addc_u32 s35, s5, 0
	global_load_dwordx4 v[116:119], v156, s[34:35]
	global_load_dwordx4 v[112:115], v156, s[34:35] offset:64
	global_load_dwordx4 v[88:91], v156, s[34:35] offset:512
	global_load_dwordx4 v[84:87], v156, s[34:35] offset:576
	s_add_u32 s36, s4, 0x1000
	s_addc_u32 s37, s5, 0
	global_store_dwordx4 v156, v[180:183], s[36:37] sc1
	global_store_dwordx4 v156, v[184:187], s[36:37] offset:64 sc1
	global_store_dwordx4 v156, v[188:191], s[36:37] offset:512 sc1
	global_store_dwordx4 v156, v[192:195], s[36:37] offset:576 sc1
	s_add_u32 s34, s4, 0x82000
	s_addc_u32 s35, s5, 0
	global_load_dwordx4 v[180:183], v156, s[34:35]
	global_load_dwordx4 v[184:187], v156, s[34:35] offset:64
	global_load_dwordx4 v[188:191], v156, s[34:35] offset:512
	global_load_dwordx4 v[192:195], v156, s[34:35] offset:576
	s_waitcnt vmcnt(24)
;     __device__ __forceinline__ void operator()(const f32x4 (&acc)[2][2][4][2], const pg8::Unit& u, int wr, int wc, int fr, int fq) const {
;     ...
;         for (int ai = 0; ai < 2; ++ai)
; #pragma unroll
;             for (int m = 0; m < 4; ++m) {
;                 const size_t off = (size_t)(row0 + ai * 128 + m * 16) * DM + col0;
; #pragma unroll
;                 for (int bj = 0; bj < 2; ++bj)
; #pragma unroll
;                     for (int n = 0; n < 2; ++n) {
;                         const f32x4 xv = *(const f32x4*)(xin + off + bj * 128 + n * 16);
;                         *(f32x4*)(out + off + bj * 128 + n * 16) = xv + gv[bj][n] * acc[ai][bj][m][n];
;                     }
;                 if (m == 3) asm volatile("" ::: "memory");
;             }
	v_pk_fma_f32 v[198:199], v[110:111], v[134:135], v[198:199]
	v_pk_fma_f32 v[196:197], v[108:109], v[132:133], v[196:197]
	v_pk_fma_f32 v[206:207], v[102:103], v[130:131], v[206:207]
	v_pk_fma_f32 v[204:205], v[100:101], v[128:129], v[204:205]
	v_pk_fma_f32 v[210:211], v[78:79], v[142:143], v[210:211]
	v_pk_fma_f32 v[208:209], v[76:77], v[140:141], v[208:209]
	v_pk_fma_f32 v[214:215], v[74:75], v[138:139], v[214:215]
	v_pk_fma_f32 v[212:213], v[72:73], v[136:137], v[212:213]
	s_add_u32 s34, s4, 0x83000
	s_addc_u32 s35, s5, 0
	global_load_dwordx4 v[108:111], v156, s[34:35]
	global_load_dwordx4 v[100:103], v156, s[34:35] offset:64
	global_load_dwordx4 v[76:79], v156, s[34:35] offset:512
	global_load_dwordx4 v[72:75], v156, s[34:35] offset:576
	s_add_u32 s36, s4, 0x2000
	s_addc_u32 s37, s5, 0
	global_store_dwordx4 v156, v[196:199], s[36:37] sc1
	global_store_dwordx4 v156, v[204:207], s[36:37] offset:64 sc1
	global_store_dwordx4 v156, v[208:211], s[36:37] offset:512 sc1
	global_store_dwordx4 v156, v[212:215], s[36:37] offset:576 sc1
	s_waitcnt vmcnt(28)
	v_pk_fma_f32 v[126:127], v[94:95], v[134:135], v[126:127]
	v_pk_fma_f32 v[124:125], v[92:93], v[132:133], v[124:125]
	v_pk_fma_f32 v[122:123], v[82:83], v[130:131], v[122:123]
	v_pk_fma_f32 v[120:121], v[80:81], v[128:129], v[120:121]
	v_pk_fma_f32 v[106:107], v[70:71], v[142:143], v[106:107]
	v_pk_fma_f32 v[104:105], v[68:69], v[140:141], v[104:105]
	v_pk_fma_f32 v[98:99], v[66:67], v[138:139], v[98:99]
	v_pk_fma_f32 v[96:97], v[64:65], v[136:137], v[96:97]
	s_add_u32 s36, s4, 0x3000
	s_addc_u32 s37, s5, 0
	global_store_dwordx4 v156, v[124:127], s[36:37] sc1
	global_store_dwordx4 v156, v[120:123], s[36:37] offset:64 sc1
	global_store_dwordx4 v156, v[104:107], s[36:37] offset:512 sc1
	global_store_dwordx4 v156, v[96:99], s[36:37] offset:576 sc1
	s_waitcnt vmcnt(24)
	v_pk_fma_f32 v[166:167], v[62:63], v[134:135], v[166:167]
	v_pk_fma_f32 v[164:165], v[60:61], v[132:133], v[164:165]
	v_pk_fma_f32 v[170:171], v[58:59], v[130:131], v[170:171]
	v_pk_fma_f32 v[168:169], v[56:57], v[128:129], v[168:169]
	v_pk_fma_f32 v[174:175], v[42:43], v[142:143], v[174:175]
	v_pk_fma_f32 v[172:173], v[40:41], v[140:141], v[172:173]
	v_pk_fma_f32 v[178:179], v[34:35], v[138:139], v[178:179]
	v_pk_fma_f32 v[176:177], v[32:33], v[136:137], v[176:177]
	s_add_u32 s36, s4, 0x80000
	s_addc_u32 s37, s5, 0
	global_store_dwordx4 v156, v[164:167], s[36:37] sc1
	global_store_dwordx4 v156, v[168:171], s[36:37] offset:64 sc1
	global_store_dwordx4 v156, v[172:175], s[36:37] offset:512 sc1
	global_store_dwordx4 v156, v[176:179], s[36:37] offset:576 sc1
	s_waitcnt vmcnt(24)
	v_pk_fma_f32 v[118:119], v[54:55], v[134:135], v[118:119]
	v_pk_fma_f32 v[116:117], v[52:53], v[132:133], v[116:117]
	v_pk_fma_f32 v[114:115], v[50:51], v[130:131], v[114:115]
	v_pk_fma_f32 v[112:113], v[48:49], v[128:129], v[112:113]
	v_pk_fma_f32 v[90:91], v[30:31], v[142:143], v[90:91]
	v_pk_fma_f32 v[88:89], v[28:29], v[140:141], v[88:89]
	v_pk_fma_f32 v[86:87], v[26:27], v[138:139], v[86:87]
	v_pk_fma_f32 v[84:85], v[24:25], v[136:137], v[84:85]
	s_add_u32 s36, s4, 0x81000
	s_addc_u32 s37, s5, 0
	global_store_dwordx4 v156, v[116:119], s[36:37] sc1
	global_store_dwordx4 v156, v[112:115], s[36:37] offset:64 sc1
	global_store_dwordx4 v156, v[88:91], s[36:37] offset:512 sc1
	global_store_dwordx4 v156, v[84:87], s[36:37] offset:576 sc1
	s_waitcnt vmcnt(20)
	v_pk_fma_f32 v[182:183], v[46:47], v[134:135], v[182:183]
	v_pk_fma_f32 v[180:181], v[44:45], v[132:133], v[180:181]
	v_pk_fma_f32 v[186:187], v[38:39], v[130:131], v[186:187]
	v_pk_fma_f32 v[184:185], v[36:37], v[128:129], v[184:185]
	v_pk_fma_f32 v[190:191], v[14:15], v[142:143], v[190:191]
	v_pk_fma_f32 v[188:189], v[12:13], v[140:141], v[188:189]
	v_pk_fma_f32 v[194:195], v[10:11], v[138:139], v[194:195]
	v_pk_fma_f32 v[192:193], v[8:9], v[136:137], v[192:193]
	s_add_u32 s36, s4, 0x82000
	s_addc_u32 s37, s5, 0
	global_store_dwordx4 v156, v[180:183], s[36:37] sc1
	global_store_dwordx4 v156, v[184:187], s[36:37] offset:64 sc1
	global_store_dwordx4 v156, v[188:191], s[36:37] offset:512 sc1
	global_store_dwordx4 v156, v[192:195], s[36:37] offset:576 sc1
	s_waitcnt vmcnt(20)
	v_pk_fma_f32 v[110:111], v[22:23], v[134:135], v[110:111]
	v_pk_fma_f32 v[108:109], v[20:21], v[132:133], v[108:109]
	v_pk_fma_f32 v[102:103], v[18:19], v[130:131], v[102:103]
	v_pk_fma_f32 v[100:101], v[16:17], v[128:129], v[100:101]
	v_pk_fma_f32 v[78:79], v[6:7], v[142:143], v[78:79]
	v_pk_fma_f32 v[76:77], v[4:5], v[140:141], v[76:77]
	v_pk_fma_f32 v[74:75], v[2:3], v[138:139], v[74:75]
	v_pk_fma_f32 v[72:73], v[0:1], v[136:137], v[72:73]
	s_add_u32 s36, s4, 0x83000
	s_addc_u32 s37, s5, 0
	global_store_dwordx4 v156, v[108:111], s[36:37] sc1
	global_store_dwordx4 v156, v[100:103], s[36:37] offset:64 sc1
	global_store_dwordx4 v156, v[76:79], s[36:37] offset:512 sc1
	global_store_dwordx4 v156, v[72:75], s[36:37] offset:576 sc1
	s_cbranch_vccnz .LBB0_1096
	s_andn2_b64 vcc, exec, s[8:9]
	s_cbranch_vccnz .LBB0_1095
	s_barrier
	s_branch .LBB0_1095
